# hand-written rg-gate epilogue (all loads up front, packed f32 math, same op order) on top of the mods GEMV batching
# speedup vs baseline: 1.0125x; 1.0070x over previous
; __device__ __forceinline__ float fsilu(float x) { return x * fsig(x); }
; __device__ __forceinline__ u32x4 pack8(const f32x4 a, const f32x4 b) { u32x4 w; w.x = pk2(a[0], a[1]); w.y = pk2(a[2], a[3]); w.z = pk2(b[0], b[1]); w.w = pk2(b[2], b[3]); return w; }
; __device__ __forceinline__ void unpack8(const u32x4 w, f32x4& a, f32x4& b) { a[0] = bflo(w.x); a[1] = bfhi(w.x); a[2] = bflo(w.y); a[3] = bfhi(w.y); b[0] = bflo(w.z); b[1] = bfhi(w.z); b[2] = bflo(w.w); b[3] = bfhi(w.w); }
;     __device__ __forceinline__ bool operator()(EPI_ARGS) const {
;             const int head = u.pn >> 1;
; #pragma unroll
;             for (int bj = 0; bj < 2; ++bj) {
;                 const int col = u.pn * 256 + COLLOC(bj);
;                 const f32x4 w0 = *(const f32x4*)(gnw + col), w1 = *(const f32x4*)(gnw + col + 4);
; #pragma unroll
;                 for (int ai = 0; ai < 2; ++ai) {
; #pragma unroll
;                     for (int mh = 0; mh < 4; mh += 2) {
;                     f32x2 st[2]; u32x4 raw[2];
; #pragma unroll
;                     for (int m2 = 0; m2 < 2; ++m2) { const size_t row = (size_t)u.pm * 256 + ROWLOC(ai, mh + m2); st[m2] = *(const f32x2*)(stats + (row * 4 + head) * 2); raw[m2] = *(const u32x4*)(o + row * 2048 + col); }
; #pragma unroll
;                     for (int m2 = 0; m2 < 2; ++m2) {
;                         const int m = mh + m2;
;                         const size_t row = (size_t)u.pm * 256 + ROWLOC(ai, m);
;                         f32x4 v0, v1; unpack8(raw[m2], v0, v1);
;                         f32x4 r0, r1;
; #pragma unroll
;                         for (int e = 0; e < 4; ++e) { r0[e] = fsilu(acc[ai][bj][m][0][e]) * ((v0[e] - st[m2].x) * st[m2].y * w0[e]); r1[e] = fsilu(acc[ai][bj][m][1][e]) * ((v1[e] - st[m2].x) * st[m2].y * w1[e]); }
;                         *(u32x4*)(o + row * 2048 + col) = pack8(r0, r1);
.LBB0_990:
	s_lshl_b32 s38, s20, 8
	s_ashr_i32 s26, s61, 1
	s_lshl_b32 s26, s26, 3
	s_add_u32 s40, s48, s26
	s_addc_u32 s41, s49, 0
	s_lshl_b32 s21, s61, 8
	s_or_b32 s21, s21, s51
	v_add_u32_e32 v116, s38, v160
	v_add_u32_e32 v116, s50, v116
	v_lshl_add_u32 v118, v161, 3, s21
	v_lshlrev_b32_e32 v117, 5, v116
	v_lshlrev_b32_e32 v119, 1, v118
	v_lshl_add_u32 v116, v116, 12, v119
	v_lshlrev_b32_e32 v118, 2, v118
	v_add_u32_e32 v119, 0x1000, v117
	global_load_dwordx4 v[140:143], v118, s[10:11]
	global_load_dwordx4 v[144:147], v118, s[10:11] offset:16
	global_load_dwordx4 v[148:151], v118, s[10:11] offset:512
	global_load_dwordx4 v[152:155], v118, s[10:11] offset:528
	global_load_dwordx2 v[242:243], v117, s[40:41]
	global_load_dwordx2 v[244:245], v117, s[40:41] offset:512
	global_load_dwordx2 v[246:247], v117, s[40:41] offset:1024
	global_load_dwordx2 v[248:249], v117, s[40:41] offset:1536
	global_load_dwordx2 v[250:251], v119, s[40:41]
	global_load_dwordx2 v[252:253], v119, s[40:41] offset:512
	global_load_dwordx2 v[112:113], v119, s[40:41] offset:1024
	global_load_dwordx2 v[114:115], v119, s[40:41] offset:1536
	global_load_dwordx4 v[178:181], v116, s[6:7]
	global_load_dwordx4 v[182:185], v116, s[6:7] offset:256
	v_add_u32_e32 v156, 0x10000, v116
	global_load_dwordx4 v[186:189], v156, s[6:7]
	global_load_dwordx4 v[190:193], v156, s[6:7] offset:256
	v_add_u32_e32 v156, 0x20000, v116
	global_load_dwordx4 v[194:197], v156, s[6:7]
	global_load_dwordx4 v[198:201], v156, s[6:7] offset:256
	v_add_u32_e32 v156, 0x30000, v116
	global_load_dwordx4 v[202:205], v156, s[6:7]
	global_load_dwordx4 v[206:209], v156, s[6:7] offset:256
	v_add_u32_e32 v156, 0x80000, v116
	global_load_dwordx4 v[210:213], v156, s[6:7]
	global_load_dwordx4 v[214:217], v156, s[6:7] offset:256
	v_add_u32_e32 v156, 0x90000, v116
	global_load_dwordx4 v[218:221], v156, s[6:7]
	global_load_dwordx4 v[222:225], v156, s[6:7] offset:256
	v_add_u32_e32 v156, 0xa0000, v116
	global_load_dwordx4 v[226:229], v156, s[6:7]
	global_load_dwordx4 v[230:233], v156, s[6:7] offset:256
	v_add_u32_e32 v156, 0xb0000, v116
	global_load_dwordx4 v[234:237], v156, s[6:7]
	global_load_dwordx4 v[238:241], v156, s[6:7] offset:256
	s_waitcnt vmcnt(15)
	v_lshlrev_b32_e32 v168, 16, v178
	v_and_b32_e32 v169, 0xffff0000, v178
	v_lshlrev_b32_e32 v170, 16, v179
	v_and_b32_e32 v171, 0xffff0000, v179
	v_mul_f32_e32 v172, 0xbfb8aa3b, v132
	v_mul_f32_e32 v173, 0xbfb8aa3b, v133
	v_mul_f32_e32 v174, 0xbfb8aa3b, v134
	v_mul_f32_e32 v175, 0xbfb8aa3b, v135
	v_exp_f32_e32 v172, v172
	v_exp_f32_e32 v173, v173
	v_exp_f32_e32 v174, v174
	v_exp_f32_e32 v175, v175
	v_pk_add_f32 v[168:169], v[168:169], v[242:243] op_sel_hi:[1,0] neg_lo:[0,1] neg_hi:[0,1]
	v_pk_add_f32 v[170:171], v[170:171], v[242:243] op_sel_hi:[1,0] neg_lo:[0,1] neg_hi:[0,1]
	v_pk_add_f32 v[172:173], v[172:173], 1.0 op_sel_hi:[1,0]
	v_pk_add_f32 v[174:175], v[174:175], 1.0 op_sel_hi:[1,0]
	v_pk_mul_f32 v[168:169], v[168:169], v[242:243] op_sel:[0,1] op_sel_hi:[1,1]
	v_pk_mul_f32 v[170:171], v[170:171], v[242:243] op_sel:[0,1] op_sel_hi:[1,1]
	v_rcp_f32_e32 v172, v172
	v_rcp_f32_e32 v173, v173
	v_rcp_f32_e32 v174, v174
	v_rcp_f32_e32 v175, v175
	v_pk_mul_f32 v[168:169], v[140:141], v[168:169]
	v_pk_mul_f32 v[170:171], v[142:143], v[170:171]
	v_pk_mul_f32 v[172:173], v[132:133], v[172:173]
	v_pk_mul_f32 v[174:175], v[134:135], v[174:175]
	v_pk_mul_f32 v[168:169], v[172:173], v[168:169]
	v_pk_mul_f32 v[170:171], v[174:175], v[170:171]
	v_cvt_pk_bf16_f32 v178, v168, v169
	v_cvt_pk_bf16_f32 v179, v170, v171
	v_lshlrev_b32_e32 v168, 16, v180
	v_and_b32_e32 v169, 0xffff0000, v180
	v_lshlrev_b32_e32 v170, 16, v181
	v_and_b32_e32 v171, 0xffff0000, v181
	v_mul_f32_e32 v172, 0xbfb8aa3b, v128
	v_mul_f32_e32 v173, 0xbfb8aa3b, v129
	v_mul_f32_e32 v174, 0xbfb8aa3b, v130
	v_mul_f32_e32 v175, 0xbfb8aa3b, v131
	v_exp_f32_e32 v172, v172
	v_exp_f32_e32 v173, v173
	v_exp_f32_e32 v174, v174
	v_exp_f32_e32 v175, v175
	v_pk_add_f32 v[168:169], v[168:169], v[242:243] op_sel_hi:[1,0] neg_lo:[0,1] neg_hi:[0,1]
	v_pk_add_f32 v[170:171], v[170:171], v[242:243] op_sel_hi:[1,0] neg_lo:[0,1] neg_hi:[0,1]
	v_pk_add_f32 v[172:173], v[172:173], 1.0 op_sel_hi:[1,0]
	v_pk_add_f32 v[174:175], v[174:175], 1.0 op_sel_hi:[1,0]
	v_pk_mul_f32 v[168:169], v[168:169], v[242:243] op_sel:[0,1] op_sel_hi:[1,1]
	v_pk_mul_f32 v[170:171], v[170:171], v[242:243] op_sel:[0,1] op_sel_hi:[1,1]
	v_rcp_f32_e32 v172, v172
	v_rcp_f32_e32 v173, v173
	v_rcp_f32_e32 v174, v174
	v_rcp_f32_e32 v175, v175
	v_pk_mul_f32 v[168:169], v[144:145], v[168:169]
	v_pk_mul_f32 v[170:171], v[146:147], v[170:171]
	v_pk_mul_f32 v[172:173], v[128:129], v[172:173]
	v_pk_mul_f32 v[174:175], v[130:131], v[174:175]
	v_pk_mul_f32 v[168:169], v[172:173], v[168:169]
	v_pk_mul_f32 v[170:171], v[174:175], v[170:171]
	v_cvt_pk_bf16_f32 v180, v168, v169
	v_cvt_pk_bf16_f32 v181, v170, v171
	global_store_dwordx4 v116, v[178:181], s[6:7]
	s_waitcnt vmcnt(15)
; __device__ __forceinline__ float fsilu(float x) { return x * fsig(x); }
; __device__ __forceinline__ u32x4 pack8(const f32x4 a, const f32x4 b) { u32x4 w; w.x = pk2(a[0], a[1]); w.y = pk2(a[2], a[3]); w.z = pk2(b[0], b[1]); w.w = pk2(b[2], b[3]); return w; }
; __device__ __forceinline__ void unpack8(const u32x4 w, f32x4& a, f32x4& b) { a[0] = bflo(w.x); a[1] = bfhi(w.x); a[2] = bflo(w.y); a[3] = bfhi(w.y); b[0] = bflo(w.z); b[1] = bfhi(w.z); b[2] = bflo(w.w); b[3] = bfhi(w.w); }
;     __device__ __forceinline__ bool operator()(EPI_ARGS) const {
;     ...
;                     for (int m2 = 0; m2 < 2; ++m2) {
;                         const int m = mh + m2;
;                         const size_t row = (size_t)u.pm * 256 + ROWLOC(ai, m);
;                         f32x4 v0, v1; unpack8(raw[m2], v0, v1);
;                         f32x4 r0, r1;
; #pragma unroll
;                         for (int e = 0; e < 4; ++e) { r0[e] = fsilu(acc[ai][bj][m][0][e]) * ((v0[e] - st[m2].x) * st[m2].y * w0[e]); r1[e] = fsilu(acc[ai][bj][m][1][e]) * ((v1[e] - st[m2].x) * st[m2].y * w1[e]); }
;                         *(u32x4*)(o + row * 2048 + col) = pack8(r0, r1);
	v_lshlrev_b32_e32 v168, 16, v182
	v_and_b32_e32 v169, 0xffff0000, v182
	v_lshlrev_b32_e32 v170, 16, v183
	v_and_b32_e32 v171, 0xffff0000, v183
	v_mul_f32_e32 v172, 0xbfb8aa3b, v60
	v_mul_f32_e32 v173, 0xbfb8aa3b, v61
	v_mul_f32_e32 v174, 0xbfb8aa3b, v62
	v_mul_f32_e32 v175, 0xbfb8aa3b, v63
	v_exp_f32_e32 v172, v172
	v_exp_f32_e32 v173, v173
	v_exp_f32_e32 v174, v174
	v_exp_f32_e32 v175, v175
	v_pk_add_f32 v[168:169], v[168:169], v[242:243] op_sel_hi:[1,0] neg_lo:[0,1] neg_hi:[0,1]
	v_pk_add_f32 v[170:171], v[170:171], v[242:243] op_sel_hi:[1,0] neg_lo:[0,1] neg_hi:[0,1]
	v_pk_add_f32 v[172:173], v[172:173], 1.0 op_sel_hi:[1,0]
	v_pk_add_f32 v[174:175], v[174:175], 1.0 op_sel_hi:[1,0]
	v_pk_mul_f32 v[168:169], v[168:169], v[242:243] op_sel:[0,1] op_sel_hi:[1,1]
	v_pk_mul_f32 v[170:171], v[170:171], v[242:243] op_sel:[0,1] op_sel_hi:[1,1]
	v_rcp_f32_e32 v172, v172
	v_rcp_f32_e32 v173, v173
	v_rcp_f32_e32 v174, v174
	v_rcp_f32_e32 v175, v175
	v_pk_mul_f32 v[168:169], v[148:149], v[168:169]
	v_pk_mul_f32 v[170:171], v[150:151], v[170:171]
	v_pk_mul_f32 v[172:173], v[60:61], v[172:173]
	v_pk_mul_f32 v[174:175], v[62:63], v[174:175]
	v_pk_mul_f32 v[168:169], v[172:173], v[168:169]
	v_pk_mul_f32 v[170:171], v[174:175], v[170:171]
	v_cvt_pk_bf16_f32 v182, v168, v169
	v_cvt_pk_bf16_f32 v183, v170, v171
	v_lshlrev_b32_e32 v168, 16, v184
	v_and_b32_e32 v169, 0xffff0000, v184
	v_lshlrev_b32_e32 v170, 16, v185
	v_and_b32_e32 v171, 0xffff0000, v185
	v_mul_f32_e32 v172, 0xbfb8aa3b, v56
	v_mul_f32_e32 v173, 0xbfb8aa3b, v57
	v_mul_f32_e32 v174, 0xbfb8aa3b, v58
	v_mul_f32_e32 v175, 0xbfb8aa3b, v59
	v_exp_f32_e32 v172, v172
	v_exp_f32_e32 v173, v173
	v_exp_f32_e32 v174, v174
	v_exp_f32_e32 v175, v175
	v_pk_add_f32 v[168:169], v[168:169], v[242:243] op_sel_hi:[1,0] neg_lo:[0,1] neg_hi:[0,1]
	v_pk_add_f32 v[170:171], v[170:171], v[242:243] op_sel_hi:[1,0] neg_lo:[0,1] neg_hi:[0,1]
	v_pk_add_f32 v[172:173], v[172:173], 1.0 op_sel_hi:[1,0]
	v_pk_add_f32 v[174:175], v[174:175], 1.0 op_sel_hi:[1,0]
	v_pk_mul_f32 v[168:169], v[168:169], v[242:243] op_sel:[0,1] op_sel_hi:[1,1]
	v_pk_mul_f32 v[170:171], v[170:171], v[242:243] op_sel:[0,1] op_sel_hi:[1,1]
	v_rcp_f32_e32 v172, v172
	v_rcp_f32_e32 v173, v173
	v_rcp_f32_e32 v174, v174
	v_rcp_f32_e32 v175, v175
	v_pk_mul_f32 v[168:169], v[152:153], v[168:169]
	v_pk_mul_f32 v[170:171], v[154:155], v[170:171]
	v_pk_mul_f32 v[172:173], v[56:57], v[172:173]
	v_pk_mul_f32 v[174:175], v[58:59], v[174:175]
	v_pk_mul_f32 v[168:169], v[172:173], v[168:169]
	v_pk_mul_f32 v[170:171], v[174:175], v[170:171]
	v_cvt_pk_bf16_f32 v184, v168, v169
	v_cvt_pk_bf16_f32 v185, v170, v171
	global_store_dwordx4 v116, v[182:185], s[6:7] offset:256
	s_waitcnt vmcnt(15)
	v_lshlrev_b32_e32 v168, 16, v186
	v_and_b32_e32 v169, 0xffff0000, v186
	v_lshlrev_b32_e32 v170, 16, v187
	v_and_b32_e32 v171, 0xffff0000, v187
	v_mul_f32_e32 v172, 0xbfb8aa3b, v124
	v_mul_f32_e32 v173, 0xbfb8aa3b, v125
	v_mul_f32_e32 v174, 0xbfb8aa3b, v126
	v_mul_f32_e32 v175, 0xbfb8aa3b, v127
	v_exp_f32_e32 v172, v172
	v_exp_f32_e32 v173, v173
	v_exp_f32_e32 v174, v174
	v_exp_f32_e32 v175, v175
	v_pk_add_f32 v[168:169], v[168:169], v[244:245] op_sel_hi:[1,0] neg_lo:[0,1] neg_hi:[0,1]
	v_pk_add_f32 v[170:171], v[170:171], v[244:245] op_sel_hi:[1,0] neg_lo:[0,1] neg_hi:[0,1]
	v_pk_add_f32 v[172:173], v[172:173], 1.0 op_sel_hi:[1,0]
	v_pk_add_f32 v[174:175], v[174:175], 1.0 op_sel_hi:[1,0]
	v_pk_mul_f32 v[168:169], v[168:169], v[244:245] op_sel:[0,1] op_sel_hi:[1,1]
	v_pk_mul_f32 v[170:171], v[170:171], v[244:245] op_sel:[0,1] op_sel_hi:[1,1]
	v_rcp_f32_e32 v172, v172
	v_rcp_f32_e32 v173, v173
	v_rcp_f32_e32 v174, v174
	v_rcp_f32_e32 v175, v175
	v_pk_mul_f32 v[168:169], v[140:141], v[168:169]
	v_pk_mul_f32 v[170:171], v[142:143], v[170:171]
	v_pk_mul_f32 v[172:173], v[124:125], v[172:173]
	v_pk_mul_f32 v[174:175], v[126:127], v[174:175]
	v_pk_mul_f32 v[168:169], v[172:173], v[168:169]
	v_pk_mul_f32 v[170:171], v[174:175], v[170:171]
	v_cvt_pk_bf16_f32 v186, v168, v169
	v_cvt_pk_bf16_f32 v187, v170, v171
	v_lshlrev_b32_e32 v168, 16, v188
	v_and_b32_e32 v169, 0xffff0000, v188
	v_lshlrev_b32_e32 v170, 16, v189
	v_and_b32_e32 v171, 0xffff0000, v189
	v_mul_f32_e32 v172, 0xbfb8aa3b, v120
	v_mul_f32_e32 v173, 0xbfb8aa3b, v121
	v_mul_f32_e32 v174, 0xbfb8aa3b, v122
	v_mul_f32_e32 v175, 0xbfb8aa3b, v123
	v_exp_f32_e32 v172, v172
	v_exp_f32_e32 v173, v173
	v_exp_f32_e32 v174, v174
	v_exp_f32_e32 v175, v175
	v_pk_add_f32 v[168:169], v[168:169], v[244:245] op_sel_hi:[1,0] neg_lo:[0,1] neg_hi:[0,1]
	v_pk_add_f32 v[170:171], v[170:171], v[244:245] op_sel_hi:[1,0] neg_lo:[0,1] neg_hi:[0,1]
	v_pk_add_f32 v[172:173], v[172:173], 1.0 op_sel_hi:[1,0]
	v_pk_add_f32 v[174:175], v[174:175], 1.0 op_sel_hi:[1,0]
	v_pk_mul_f32 v[168:169], v[168:169], v[244:245] op_sel:[0,1] op_sel_hi:[1,1]
	v_pk_mul_f32 v[170:171], v[170:171], v[244:245] op_sel:[0,1] op_sel_hi:[1,1]
	v_rcp_f32_e32 v172, v172
	v_rcp_f32_e32 v173, v173
	v_rcp_f32_e32 v174, v174
	v_rcp_f32_e32 v175, v175
	v_pk_mul_f32 v[168:169], v[144:145], v[168:169]
	v_pk_mul_f32 v[170:171], v[146:147], v[170:171]
	v_pk_mul_f32 v[172:173], v[120:121], v[172:173]
	v_pk_mul_f32 v[174:175], v[122:123], v[174:175]
	v_pk_mul_f32 v[168:169], v[172:173], v[168:169]
	v_pk_mul_f32 v[170:171], v[174:175], v[170:171]
	v_cvt_pk_bf16_f32 v188, v168, v169
	v_cvt_pk_bf16_f32 v189, v170, v171
	v_add_u32_e32 v156, 0x10000, v116
	global_store_dwordx4 v156, v[186:189], s[6:7]
	s_waitcnt vmcnt(15)
; __device__ __forceinline__ float fsilu(float x) { return x * fsig(x); }
; __device__ __forceinline__ u32x4 pack8(const f32x4 a, const f32x4 b) { u32x4 w; w.x = pk2(a[0], a[1]); w.y = pk2(a[2], a[3]); w.z = pk2(b[0], b[1]); w.w = pk2(b[2], b[3]); return w; }
; __device__ __forceinline__ void unpack8(const u32x4 w, f32x4& a, f32x4& b) { a[0] = bflo(w.x); a[1] = bfhi(w.x); a[2] = bflo(w.y); a[3] = bfhi(w.y); b[0] = bflo(w.z); b[1] = bfhi(w.z); b[2] = bflo(w.w); b[3] = bfhi(w.w); }
;     __device__ __forceinline__ bool operator()(EPI_ARGS) const {
;     ...
;                     for (int m2 = 0; m2 < 2; ++m2) {
;                         const int m = mh + m2;
;                         const size_t row = (size_t)u.pm * 256 + ROWLOC(ai, m);
;                         f32x4 v0, v1; unpack8(raw[m2], v0, v1);
;                         f32x4 r0, r1;
; #pragma unroll
;                         for (int e = 0; e < 4; ++e) { r0[e] = fsilu(acc[ai][bj][m][0][e]) * ((v0[e] - st[m2].x) * st[m2].y * w0[e]); r1[e] = fsilu(acc[ai][bj][m][1][e]) * ((v1[e] - st[m2].x) * st[m2].y * w1[e]); }
;                         *(u32x4*)(o + row * 2048 + col) = pack8(r0, r1);
	v_lshlrev_b32_e32 v168, 16, v190
	v_and_b32_e32 v169, 0xffff0000, v190
	v_lshlrev_b32_e32 v170, 16, v191
	v_and_b32_e32 v171, 0xffff0000, v191
	v_mul_f32_e32 v172, 0xbfb8aa3b, v52
	v_mul_f32_e32 v173, 0xbfb8aa3b, v53
	v_mul_f32_e32 v174, 0xbfb8aa3b, v54
	v_mul_f32_e32 v175, 0xbfb8aa3b, v55
	v_exp_f32_e32 v172, v172
	v_exp_f32_e32 v173, v173
	v_exp_f32_e32 v174, v174
	v_exp_f32_e32 v175, v175
	v_pk_add_f32 v[168:169], v[168:169], v[244:245] op_sel_hi:[1,0] neg_lo:[0,1] neg_hi:[0,1]
	v_pk_add_f32 v[170:171], v[170:171], v[244:245] op_sel_hi:[1,0] neg_lo:[0,1] neg_hi:[0,1]
	v_pk_add_f32 v[172:173], v[172:173], 1.0 op_sel_hi:[1,0]
	v_pk_add_f32 v[174:175], v[174:175], 1.0 op_sel_hi:[1,0]
	v_pk_mul_f32 v[168:169], v[168:169], v[244:245] op_sel:[0,1] op_sel_hi:[1,1]
	v_pk_mul_f32 v[170:171], v[170:171], v[244:245] op_sel:[0,1] op_sel_hi:[1,1]
	v_rcp_f32_e32 v172, v172
	v_rcp_f32_e32 v173, v173
	v_rcp_f32_e32 v174, v174
	v_rcp_f32_e32 v175, v175
	v_pk_mul_f32 v[168:169], v[148:149], v[168:169]
	v_pk_mul_f32 v[170:171], v[150:151], v[170:171]
	v_pk_mul_f32 v[172:173], v[52:53], v[172:173]
	v_pk_mul_f32 v[174:175], v[54:55], v[174:175]
	v_pk_mul_f32 v[168:169], v[172:173], v[168:169]
	v_pk_mul_f32 v[170:171], v[174:175], v[170:171]
	v_cvt_pk_bf16_f32 v190, v168, v169
	v_cvt_pk_bf16_f32 v191, v170, v171
	v_lshlrev_b32_e32 v168, 16, v192
	v_and_b32_e32 v169, 0xffff0000, v192
	v_lshlrev_b32_e32 v170, 16, v193
	v_and_b32_e32 v171, 0xffff0000, v193
	v_mul_f32_e32 v172, 0xbfb8aa3b, v48
	v_mul_f32_e32 v173, 0xbfb8aa3b, v49
	v_mul_f32_e32 v174, 0xbfb8aa3b, v50
	v_mul_f32_e32 v175, 0xbfb8aa3b, v51
	v_exp_f32_e32 v172, v172
	v_exp_f32_e32 v173, v173
	v_exp_f32_e32 v174, v174
	v_exp_f32_e32 v175, v175
	v_pk_add_f32 v[168:169], v[168:169], v[244:245] op_sel_hi:[1,0] neg_lo:[0,1] neg_hi:[0,1]
	v_pk_add_f32 v[170:171], v[170:171], v[244:245] op_sel_hi:[1,0] neg_lo:[0,1] neg_hi:[0,1]
	v_pk_add_f32 v[172:173], v[172:173], 1.0 op_sel_hi:[1,0]
	v_pk_add_f32 v[174:175], v[174:175], 1.0 op_sel_hi:[1,0]
	v_pk_mul_f32 v[168:169], v[168:169], v[244:245] op_sel:[0,1] op_sel_hi:[1,1]
	v_pk_mul_f32 v[170:171], v[170:171], v[244:245] op_sel:[0,1] op_sel_hi:[1,1]
	v_rcp_f32_e32 v172, v172
	v_rcp_f32_e32 v173, v173
	v_rcp_f32_e32 v174, v174
	v_rcp_f32_e32 v175, v175
	v_pk_mul_f32 v[168:169], v[152:153], v[168:169]
	v_pk_mul_f32 v[170:171], v[154:155], v[170:171]
	v_pk_mul_f32 v[172:173], v[48:49], v[172:173]
	v_pk_mul_f32 v[174:175], v[50:51], v[174:175]
	v_pk_mul_f32 v[168:169], v[172:173], v[168:169]
	v_pk_mul_f32 v[170:171], v[174:175], v[170:171]
	v_cvt_pk_bf16_f32 v192, v168, v169
	v_cvt_pk_bf16_f32 v193, v170, v171
	v_add_u32_e32 v156, 0x10000, v116
	global_store_dwordx4 v156, v[190:193], s[6:7] offset:256
	s_waitcnt vmcnt(15)
	v_lshlrev_b32_e32 v168, 16, v194
	v_and_b32_e32 v169, 0xffff0000, v194
	v_lshlrev_b32_e32 v170, 16, v195
	v_and_b32_e32 v171, 0xffff0000, v195
	v_mul_f32_e32 v172, 0xbfb8aa3b, v108
	v_mul_f32_e32 v173, 0xbfb8aa3b, v109
	v_mul_f32_e32 v174, 0xbfb8aa3b, v110
	v_mul_f32_e32 v175, 0xbfb8aa3b, v111
	v_exp_f32_e32 v172, v172
	v_exp_f32_e32 v173, v173
	v_exp_f32_e32 v174, v174
	v_exp_f32_e32 v175, v175
	v_pk_add_f32 v[168:169], v[168:169], v[246:247] op_sel_hi:[1,0] neg_lo:[0,1] neg_hi:[0,1]
	v_pk_add_f32 v[170:171], v[170:171], v[246:247] op_sel_hi:[1,0] neg_lo:[0,1] neg_hi:[0,1]
	v_pk_add_f32 v[172:173], v[172:173], 1.0 op_sel_hi:[1,0]
	v_pk_add_f32 v[174:175], v[174:175], 1.0 op_sel_hi:[1,0]
	v_pk_mul_f32 v[168:169], v[168:169], v[246:247] op_sel:[0,1] op_sel_hi:[1,1]
	v_pk_mul_f32 v[170:171], v[170:171], v[246:247] op_sel:[0,1] op_sel_hi:[1,1]
	v_rcp_f32_e32 v172, v172
	v_rcp_f32_e32 v173, v173
	v_rcp_f32_e32 v174, v174
	v_rcp_f32_e32 v175, v175
	v_pk_mul_f32 v[168:169], v[140:141], v[168:169]
	v_pk_mul_f32 v[170:171], v[142:143], v[170:171]
	v_pk_mul_f32 v[172:173], v[108:109], v[172:173]
	v_pk_mul_f32 v[174:175], v[110:111], v[174:175]
	v_pk_mul_f32 v[168:169], v[172:173], v[168:169]
	v_pk_mul_f32 v[170:171], v[174:175], v[170:171]
	v_cvt_pk_bf16_f32 v194, v168, v169
	v_cvt_pk_bf16_f32 v195, v170, v171
	v_lshlrev_b32_e32 v168, 16, v196
	v_and_b32_e32 v169, 0xffff0000, v196
	v_lshlrev_b32_e32 v170, 16, v197
	v_and_b32_e32 v171, 0xffff0000, v197
	v_mul_f32_e32 v172, 0xbfb8aa3b, v104
	v_mul_f32_e32 v173, 0xbfb8aa3b, v105
	v_mul_f32_e32 v174, 0xbfb8aa3b, v106
	v_mul_f32_e32 v175, 0xbfb8aa3b, v107
	v_exp_f32_e32 v172, v172
	v_exp_f32_e32 v173, v173
	v_exp_f32_e32 v174, v174
	v_exp_f32_e32 v175, v175
	v_pk_add_f32 v[168:169], v[168:169], v[246:247] op_sel_hi:[1,0] neg_lo:[0,1] neg_hi:[0,1]
	v_pk_add_f32 v[170:171], v[170:171], v[246:247] op_sel_hi:[1,0] neg_lo:[0,1] neg_hi:[0,1]
	v_pk_add_f32 v[172:173], v[172:173], 1.0 op_sel_hi:[1,0]
	v_pk_add_f32 v[174:175], v[174:175], 1.0 op_sel_hi:[1,0]
	v_pk_mul_f32 v[168:169], v[168:169], v[246:247] op_sel:[0,1] op_sel_hi:[1,1]
	v_pk_mul_f32 v[170:171], v[170:171], v[246:247] op_sel:[0,1] op_sel_hi:[1,1]
	v_rcp_f32_e32 v172, v172
	v_rcp_f32_e32 v173, v173
	v_rcp_f32_e32 v174, v174
	v_rcp_f32_e32 v175, v175
	v_pk_mul_f32 v[168:169], v[144:145], v[168:169]
	v_pk_mul_f32 v[170:171], v[146:147], v[170:171]
	v_pk_mul_f32 v[172:173], v[104:105], v[172:173]
	v_pk_mul_f32 v[174:175], v[106:107], v[174:175]
	v_pk_mul_f32 v[168:169], v[172:173], v[168:169]
	v_pk_mul_f32 v[170:171], v[174:175], v[170:171]
	v_cvt_pk_bf16_f32 v196, v168, v169
	v_cvt_pk_bf16_f32 v197, v170, v171
	v_add_u32_e32 v156, 0x20000, v116
	global_store_dwordx4 v156, v[194:197], s[6:7]
	s_waitcnt vmcnt(15)
; __device__ __forceinline__ float fsilu(float x) { return x * fsig(x); }
; __device__ __forceinline__ u32x4 pack8(const f32x4 a, const f32x4 b) { u32x4 w; w.x = pk2(a[0], a[1]); w.y = pk2(a[2], a[3]); w.z = pk2(b[0], b[1]); w.w = pk2(b[2], b[3]); return w; }
; __device__ __forceinline__ void unpack8(const u32x4 w, f32x4& a, f32x4& b) { a[0] = bflo(w.x); a[1] = bfhi(w.x); a[2] = bflo(w.y); a[3] = bfhi(w.y); b[0] = bflo(w.z); b[1] = bfhi(w.z); b[2] = bflo(w.w); b[3] = bfhi(w.w); }
;     __device__ __forceinline__ bool operator()(EPI_ARGS) const {
;     ...
;                     for (int m2 = 0; m2 < 2; ++m2) {
;                         const int m = mh + m2;
;                         const size_t row = (size_t)u.pm * 256 + ROWLOC(ai, m);
;                         f32x4 v0, v1; unpack8(raw[m2], v0, v1);
;                         f32x4 r0, r1;
; #pragma unroll
;                         for (int e = 0; e < 4; ++e) { r0[e] = fsilu(acc[ai][bj][m][0][e]) * ((v0[e] - st[m2].x) * st[m2].y * w0[e]); r1[e] = fsilu(acc[ai][bj][m][1][e]) * ((v1[e] - st[m2].x) * st[m2].y * w1[e]); }
;                         *(u32x4*)(o + row * 2048 + col) = pack8(r0, r1);
	v_lshlrev_b32_e32 v168, 16, v198
	v_and_b32_e32 v169, 0xffff0000, v198
	v_lshlrev_b32_e32 v170, 16, v199
	v_and_b32_e32 v171, 0xffff0000, v199
	v_mul_f32_e32 v172, 0xbfb8aa3b, v44
	v_mul_f32_e32 v173, 0xbfb8aa3b, v45
	v_mul_f32_e32 v174, 0xbfb8aa3b, v46
	v_mul_f32_e32 v175, 0xbfb8aa3b, v47
	v_exp_f32_e32 v172, v172
	v_exp_f32_e32 v173, v173
	v_exp_f32_e32 v174, v174
	v_exp_f32_e32 v175, v175
	v_pk_add_f32 v[168:169], v[168:169], v[246:247] op_sel_hi:[1,0] neg_lo:[0,1] neg_hi:[0,1]
	v_pk_add_f32 v[170:171], v[170:171], v[246:247] op_sel_hi:[1,0] neg_lo:[0,1] neg_hi:[0,1]
	v_pk_add_f32 v[172:173], v[172:173], 1.0 op_sel_hi:[1,0]
	v_pk_add_f32 v[174:175], v[174:175], 1.0 op_sel_hi:[1,0]
	v_pk_mul_f32 v[168:169], v[168:169], v[246:247] op_sel:[0,1] op_sel_hi:[1,1]
	v_pk_mul_f32 v[170:171], v[170:171], v[246:247] op_sel:[0,1] op_sel_hi:[1,1]
	v_rcp_f32_e32 v172, v172
	v_rcp_f32_e32 v173, v173
	v_rcp_f32_e32 v174, v174
	v_rcp_f32_e32 v175, v175
	v_pk_mul_f32 v[168:169], v[148:149], v[168:169]
	v_pk_mul_f32 v[170:171], v[150:151], v[170:171]
	v_pk_mul_f32 v[172:173], v[44:45], v[172:173]
	v_pk_mul_f32 v[174:175], v[46:47], v[174:175]
	v_pk_mul_f32 v[168:169], v[172:173], v[168:169]
	v_pk_mul_f32 v[170:171], v[174:175], v[170:171]
	v_cvt_pk_bf16_f32 v198, v168, v169
	v_cvt_pk_bf16_f32 v199, v170, v171
	v_lshlrev_b32_e32 v168, 16, v200
	v_and_b32_e32 v169, 0xffff0000, v200
	v_lshlrev_b32_e32 v170, 16, v201
	v_and_b32_e32 v171, 0xffff0000, v201
	v_mul_f32_e32 v172, 0xbfb8aa3b, v40
	v_mul_f32_e32 v173, 0xbfb8aa3b, v41
	v_mul_f32_e32 v174, 0xbfb8aa3b, v42
	v_mul_f32_e32 v175, 0xbfb8aa3b, v43
	v_exp_f32_e32 v172, v172
	v_exp_f32_e32 v173, v173
	v_exp_f32_e32 v174, v174
	v_exp_f32_e32 v175, v175
	v_pk_add_f32 v[168:169], v[168:169], v[246:247] op_sel_hi:[1,0] neg_lo:[0,1] neg_hi:[0,1]
	v_pk_add_f32 v[170:171], v[170:171], v[246:247] op_sel_hi:[1,0] neg_lo:[0,1] neg_hi:[0,1]
	v_pk_add_f32 v[172:173], v[172:173], 1.0 op_sel_hi:[1,0]
	v_pk_add_f32 v[174:175], v[174:175], 1.0 op_sel_hi:[1,0]
	v_pk_mul_f32 v[168:169], v[168:169], v[246:247] op_sel:[0,1] op_sel_hi:[1,1]
	v_pk_mul_f32 v[170:171], v[170:171], v[246:247] op_sel:[0,1] op_sel_hi:[1,1]
	v_rcp_f32_e32 v172, v172
	v_rcp_f32_e32 v173, v173
	v_rcp_f32_e32 v174, v174
	v_rcp_f32_e32 v175, v175
	v_pk_mul_f32 v[168:169], v[152:153], v[168:169]
	v_pk_mul_f32 v[170:171], v[154:155], v[170:171]
	v_pk_mul_f32 v[172:173], v[40:41], v[172:173]
	v_pk_mul_f32 v[174:175], v[42:43], v[174:175]
	v_pk_mul_f32 v[168:169], v[172:173], v[168:169]
	v_pk_mul_f32 v[170:171], v[174:175], v[170:171]
	v_cvt_pk_bf16_f32 v200, v168, v169
	v_cvt_pk_bf16_f32 v201, v170, v171
	v_add_u32_e32 v156, 0x20000, v116
	global_store_dwordx4 v156, v[198:201], s[6:7] offset:256
	s_waitcnt vmcnt(15)
	v_lshlrev_b32_e32 v168, 16, v202
	v_and_b32_e32 v169, 0xffff0000, v202
	v_lshlrev_b32_e32 v170, 16, v203
	v_and_b32_e32 v171, 0xffff0000, v203
	v_mul_f32_e32 v172, 0xbfb8aa3b, v100
	v_mul_f32_e32 v173, 0xbfb8aa3b, v101
	v_mul_f32_e32 v174, 0xbfb8aa3b, v102
	v_mul_f32_e32 v175, 0xbfb8aa3b, v103
	v_exp_f32_e32 v172, v172
	v_exp_f32_e32 v173, v173
	v_exp_f32_e32 v174, v174
	v_exp_f32_e32 v175, v175
	v_pk_add_f32 v[168:169], v[168:169], v[248:249] op_sel_hi:[1,0] neg_lo:[0,1] neg_hi:[0,1]
	v_pk_add_f32 v[170:171], v[170:171], v[248:249] op_sel_hi:[1,0] neg_lo:[0,1] neg_hi:[0,1]
	v_pk_add_f32 v[172:173], v[172:173], 1.0 op_sel_hi:[1,0]
	v_pk_add_f32 v[174:175], v[174:175], 1.0 op_sel_hi:[1,0]
	v_pk_mul_f32 v[168:169], v[168:169], v[248:249] op_sel:[0,1] op_sel_hi:[1,1]
	v_pk_mul_f32 v[170:171], v[170:171], v[248:249] op_sel:[0,1] op_sel_hi:[1,1]
	v_rcp_f32_e32 v172, v172
	v_rcp_f32_e32 v173, v173
	v_rcp_f32_e32 v174, v174
	v_rcp_f32_e32 v175, v175
	v_pk_mul_f32 v[168:169], v[140:141], v[168:169]
	v_pk_mul_f32 v[170:171], v[142:143], v[170:171]
	v_pk_mul_f32 v[172:173], v[100:101], v[172:173]
	v_pk_mul_f32 v[174:175], v[102:103], v[174:175]
	v_pk_mul_f32 v[168:169], v[172:173], v[168:169]
	v_pk_mul_f32 v[170:171], v[174:175], v[170:171]
	v_cvt_pk_bf16_f32 v202, v168, v169
	v_cvt_pk_bf16_f32 v203, v170, v171
	v_lshlrev_b32_e32 v168, 16, v204
	v_and_b32_e32 v169, 0xffff0000, v204
	v_lshlrev_b32_e32 v170, 16, v205
	v_and_b32_e32 v171, 0xffff0000, v205
	v_mul_f32_e32 v172, 0xbfb8aa3b, v96
	v_mul_f32_e32 v173, 0xbfb8aa3b, v97
	v_mul_f32_e32 v174, 0xbfb8aa3b, v98
	v_mul_f32_e32 v175, 0xbfb8aa3b, v99
	v_exp_f32_e32 v172, v172
	v_exp_f32_e32 v173, v173
	v_exp_f32_e32 v174, v174
	v_exp_f32_e32 v175, v175
	v_pk_add_f32 v[168:169], v[168:169], v[248:249] op_sel_hi:[1,0] neg_lo:[0,1] neg_hi:[0,1]
	v_pk_add_f32 v[170:171], v[170:171], v[248:249] op_sel_hi:[1,0] neg_lo:[0,1] neg_hi:[0,1]
	v_pk_add_f32 v[172:173], v[172:173], 1.0 op_sel_hi:[1,0]
	v_pk_add_f32 v[174:175], v[174:175], 1.0 op_sel_hi:[1,0]
	v_pk_mul_f32 v[168:169], v[168:169], v[248:249] op_sel:[0,1] op_sel_hi:[1,1]
	v_pk_mul_f32 v[170:171], v[170:171], v[248:249] op_sel:[0,1] op_sel_hi:[1,1]
	v_rcp_f32_e32 v172, v172
	v_rcp_f32_e32 v173, v173
	v_rcp_f32_e32 v174, v174
	v_rcp_f32_e32 v175, v175
	v_pk_mul_f32 v[168:169], v[144:145], v[168:169]
	v_pk_mul_f32 v[170:171], v[146:147], v[170:171]
	v_pk_mul_f32 v[172:173], v[96:97], v[172:173]
	v_pk_mul_f32 v[174:175], v[98:99], v[174:175]
	v_pk_mul_f32 v[168:169], v[172:173], v[168:169]
	v_pk_mul_f32 v[170:171], v[174:175], v[170:171]
	v_cvt_pk_bf16_f32 v204, v168, v169
	v_cvt_pk_bf16_f32 v205, v170, v171
	v_add_u32_e32 v156, 0x30000, v116
	global_store_dwordx4 v156, v[202:205], s[6:7]
	s_waitcnt vmcnt(15)
; __device__ __forceinline__ float fsilu(float x) { return x * fsig(x); }
; __device__ __forceinline__ u32x4 pack8(const f32x4 a, const f32x4 b) { u32x4 w; w.x = pk2(a[0], a[1]); w.y = pk2(a[2], a[3]); w.z = pk2(b[0], b[1]); w.w = pk2(b[2], b[3]); return w; }
; __device__ __forceinline__ void unpack8(const u32x4 w, f32x4& a, f32x4& b) { a[0] = bflo(w.x); a[1] = bfhi(w.x); a[2] = bflo(w.y); a[3] = bfhi(w.y); b[0] = bflo(w.z); b[1] = bfhi(w.z); b[2] = bflo(w.w); b[3] = bfhi(w.w); }
;     __device__ __forceinline__ bool operator()(EPI_ARGS) const {
;     ...
;                     for (int m2 = 0; m2 < 2; ++m2) {
;                         const int m = mh + m2;
;                         const size_t row = (size_t)u.pm * 256 + ROWLOC(ai, m);
;                         f32x4 v0, v1; unpack8(raw[m2], v0, v1);
;                         f32x4 r0, r1;
; #pragma unroll
;                         for (int e = 0; e < 4; ++e) { r0[e] = fsilu(acc[ai][bj][m][0][e]) * ((v0[e] - st[m2].x) * st[m2].y * w0[e]); r1[e] = fsilu(acc[ai][bj][m][1][e]) * ((v1[e] - st[m2].x) * st[m2].y * w1[e]); }
;                         *(u32x4*)(o + row * 2048 + col) = pack8(r0, r1);
	v_lshlrev_b32_e32 v168, 16, v206
	v_and_b32_e32 v169, 0xffff0000, v206
	v_lshlrev_b32_e32 v170, 16, v207
	v_and_b32_e32 v171, 0xffff0000, v207
	v_mul_f32_e32 v172, 0xbfb8aa3b, v36
	v_mul_f32_e32 v173, 0xbfb8aa3b, v37
	v_mul_f32_e32 v174, 0xbfb8aa3b, v38
	v_mul_f32_e32 v175, 0xbfb8aa3b, v39
	v_exp_f32_e32 v172, v172
	v_exp_f32_e32 v173, v173
	v_exp_f32_e32 v174, v174
	v_exp_f32_e32 v175, v175
	v_pk_add_f32 v[168:169], v[168:169], v[248:249] op_sel_hi:[1,0] neg_lo:[0,1] neg_hi:[0,1]
	v_pk_add_f32 v[170:171], v[170:171], v[248:249] op_sel_hi:[1,0] neg_lo:[0,1] neg_hi:[0,1]
	v_pk_add_f32 v[172:173], v[172:173], 1.0 op_sel_hi:[1,0]
	v_pk_add_f32 v[174:175], v[174:175], 1.0 op_sel_hi:[1,0]
	v_pk_mul_f32 v[168:169], v[168:169], v[248:249] op_sel:[0,1] op_sel_hi:[1,1]
	v_pk_mul_f32 v[170:171], v[170:171], v[248:249] op_sel:[0,1] op_sel_hi:[1,1]
	v_rcp_f32_e32 v172, v172
	v_rcp_f32_e32 v173, v173
	v_rcp_f32_e32 v174, v174
	v_rcp_f32_e32 v175, v175
	v_pk_mul_f32 v[168:169], v[148:149], v[168:169]
	v_pk_mul_f32 v[170:171], v[150:151], v[170:171]
	v_pk_mul_f32 v[172:173], v[36:37], v[172:173]
	v_pk_mul_f32 v[174:175], v[38:39], v[174:175]
	v_pk_mul_f32 v[168:169], v[172:173], v[168:169]
	v_pk_mul_f32 v[170:171], v[174:175], v[170:171]
	v_cvt_pk_bf16_f32 v206, v168, v169
	v_cvt_pk_bf16_f32 v207, v170, v171
	v_lshlrev_b32_e32 v168, 16, v208
	v_and_b32_e32 v169, 0xffff0000, v208
	v_lshlrev_b32_e32 v170, 16, v209
	v_and_b32_e32 v171, 0xffff0000, v209
	v_mul_f32_e32 v172, 0xbfb8aa3b, v32
	v_mul_f32_e32 v173, 0xbfb8aa3b, v33
	v_mul_f32_e32 v174, 0xbfb8aa3b, v34
	v_mul_f32_e32 v175, 0xbfb8aa3b, v35
	v_exp_f32_e32 v172, v172
	v_exp_f32_e32 v173, v173
	v_exp_f32_e32 v174, v174
	v_exp_f32_e32 v175, v175
	v_pk_add_f32 v[168:169], v[168:169], v[248:249] op_sel_hi:[1,0] neg_lo:[0,1] neg_hi:[0,1]
	v_pk_add_f32 v[170:171], v[170:171], v[248:249] op_sel_hi:[1,0] neg_lo:[0,1] neg_hi:[0,1]
	v_pk_add_f32 v[172:173], v[172:173], 1.0 op_sel_hi:[1,0]
	v_pk_add_f32 v[174:175], v[174:175], 1.0 op_sel_hi:[1,0]
	v_pk_mul_f32 v[168:169], v[168:169], v[248:249] op_sel:[0,1] op_sel_hi:[1,1]
	v_pk_mul_f32 v[170:171], v[170:171], v[248:249] op_sel:[0,1] op_sel_hi:[1,1]
	v_rcp_f32_e32 v172, v172
	v_rcp_f32_e32 v173, v173
	v_rcp_f32_e32 v174, v174
	v_rcp_f32_e32 v175, v175
	v_pk_mul_f32 v[168:169], v[152:153], v[168:169]
	v_pk_mul_f32 v[170:171], v[154:155], v[170:171]
	v_pk_mul_f32 v[172:173], v[32:33], v[172:173]
	v_pk_mul_f32 v[174:175], v[34:35], v[174:175]
	v_pk_mul_f32 v[168:169], v[172:173], v[168:169]
	v_pk_mul_f32 v[170:171], v[174:175], v[170:171]
	v_cvt_pk_bf16_f32 v208, v168, v169
	v_cvt_pk_bf16_f32 v209, v170, v171
	v_add_u32_e32 v156, 0x30000, v116
	global_store_dwordx4 v156, v[206:209], s[6:7] offset:256
	s_waitcnt vmcnt(15)
	v_lshlrev_b32_e32 v168, 16, v210
	v_and_b32_e32 v169, 0xffff0000, v210
	v_lshlrev_b32_e32 v170, 16, v211
	v_and_b32_e32 v171, 0xffff0000, v211
	v_mul_f32_e32 v172, 0xbfb8aa3b, v92
	v_mul_f32_e32 v173, 0xbfb8aa3b, v93
	v_mul_f32_e32 v174, 0xbfb8aa3b, v94
	v_mul_f32_e32 v175, 0xbfb8aa3b, v95
	v_exp_f32_e32 v172, v172
	v_exp_f32_e32 v173, v173
	v_exp_f32_e32 v174, v174
	v_exp_f32_e32 v175, v175
	v_pk_add_f32 v[168:169], v[168:169], v[250:251] op_sel_hi:[1,0] neg_lo:[0,1] neg_hi:[0,1]
	v_pk_add_f32 v[170:171], v[170:171], v[250:251] op_sel_hi:[1,0] neg_lo:[0,1] neg_hi:[0,1]
	v_pk_add_f32 v[172:173], v[172:173], 1.0 op_sel_hi:[1,0]
	v_pk_add_f32 v[174:175], v[174:175], 1.0 op_sel_hi:[1,0]
	v_pk_mul_f32 v[168:169], v[168:169], v[250:251] op_sel:[0,1] op_sel_hi:[1,1]
	v_pk_mul_f32 v[170:171], v[170:171], v[250:251] op_sel:[0,1] op_sel_hi:[1,1]
	v_rcp_f32_e32 v172, v172
	v_rcp_f32_e32 v173, v173
	v_rcp_f32_e32 v174, v174
	v_rcp_f32_e32 v175, v175
	v_pk_mul_f32 v[168:169], v[140:141], v[168:169]
	v_pk_mul_f32 v[170:171], v[142:143], v[170:171]
	v_pk_mul_f32 v[172:173], v[92:93], v[172:173]
	v_pk_mul_f32 v[174:175], v[94:95], v[174:175]
	v_pk_mul_f32 v[168:169], v[172:173], v[168:169]
	v_pk_mul_f32 v[170:171], v[174:175], v[170:171]
	v_cvt_pk_bf16_f32 v210, v168, v169
	v_cvt_pk_bf16_f32 v211, v170, v171
	v_lshlrev_b32_e32 v168, 16, v212
	v_and_b32_e32 v169, 0xffff0000, v212
	v_lshlrev_b32_e32 v170, 16, v213
	v_and_b32_e32 v171, 0xffff0000, v213
	v_mul_f32_e32 v172, 0xbfb8aa3b, v88
	v_mul_f32_e32 v173, 0xbfb8aa3b, v89
	v_mul_f32_e32 v174, 0xbfb8aa3b, v90
	v_mul_f32_e32 v175, 0xbfb8aa3b, v91
	v_exp_f32_e32 v172, v172
	v_exp_f32_e32 v173, v173
	v_exp_f32_e32 v174, v174
	v_exp_f32_e32 v175, v175
	v_pk_add_f32 v[168:169], v[168:169], v[250:251] op_sel_hi:[1,0] neg_lo:[0,1] neg_hi:[0,1]
	v_pk_add_f32 v[170:171], v[170:171], v[250:251] op_sel_hi:[1,0] neg_lo:[0,1] neg_hi:[0,1]
	v_pk_add_f32 v[172:173], v[172:173], 1.0 op_sel_hi:[1,0]
	v_pk_add_f32 v[174:175], v[174:175], 1.0 op_sel_hi:[1,0]
	v_pk_mul_f32 v[168:169], v[168:169], v[250:251] op_sel:[0,1] op_sel_hi:[1,1]
	v_pk_mul_f32 v[170:171], v[170:171], v[250:251] op_sel:[0,1] op_sel_hi:[1,1]
	v_rcp_f32_e32 v172, v172
	v_rcp_f32_e32 v173, v173
	v_rcp_f32_e32 v174, v174
	v_rcp_f32_e32 v175, v175
	v_pk_mul_f32 v[168:169], v[144:145], v[168:169]
	v_pk_mul_f32 v[170:171], v[146:147], v[170:171]
	v_pk_mul_f32 v[172:173], v[88:89], v[172:173]
	v_pk_mul_f32 v[174:175], v[90:91], v[174:175]
	v_pk_mul_f32 v[168:169], v[172:173], v[168:169]
	v_pk_mul_f32 v[170:171], v[174:175], v[170:171]
	v_cvt_pk_bf16_f32 v212, v168, v169
	v_cvt_pk_bf16_f32 v213, v170, v171
	v_add_u32_e32 v156, 0x80000, v116
	global_store_dwordx4 v156, v[210:213], s[6:7]
	s_waitcnt vmcnt(15)
; __device__ __forceinline__ float fsilu(float x) { return x * fsig(x); }
; __device__ __forceinline__ u32x4 pack8(const f32x4 a, const f32x4 b) { u32x4 w; w.x = pk2(a[0], a[1]); w.y = pk2(a[2], a[3]); w.z = pk2(b[0], b[1]); w.w = pk2(b[2], b[3]); return w; }
; __device__ __forceinline__ void unpack8(const u32x4 w, f32x4& a, f32x4& b) { a[0] = bflo(w.x); a[1] = bfhi(w.x); a[2] = bflo(w.y); a[3] = bfhi(w.y); b[0] = bflo(w.z); b[1] = bfhi(w.z); b[2] = bflo(w.w); b[3] = bfhi(w.w); }
;     __device__ __forceinline__ bool operator()(EPI_ARGS) const {
;     ...
;                     for (int m2 = 0; m2 < 2; ++m2) {
;                         const int m = mh + m2;
;                         const size_t row = (size_t)u.pm * 256 + ROWLOC(ai, m);
;                         f32x4 v0, v1; unpack8(raw[m2], v0, v1);
;                         f32x4 r0, r1;
; #pragma unroll
;                         for (int e = 0; e < 4; ++e) { r0[e] = fsilu(acc[ai][bj][m][0][e]) * ((v0[e] - st[m2].x) * st[m2].y * w0[e]); r1[e] = fsilu(acc[ai][bj][m][1][e]) * ((v1[e] - st[m2].x) * st[m2].y * w1[e]); }
;                         *(u32x4*)(o + row * 2048 + col) = pack8(r0, r1);
	v_lshlrev_b32_e32 v168, 16, v214
	v_and_b32_e32 v169, 0xffff0000, v214
	v_lshlrev_b32_e32 v170, 16, v215
	v_and_b32_e32 v171, 0xffff0000, v215
	v_mul_f32_e32 v172, 0xbfb8aa3b, v28
	v_mul_f32_e32 v173, 0xbfb8aa3b, v29
	v_mul_f32_e32 v174, 0xbfb8aa3b, v30
	v_mul_f32_e32 v175, 0xbfb8aa3b, v31
	v_exp_f32_e32 v172, v172
	v_exp_f32_e32 v173, v173
	v_exp_f32_e32 v174, v174
	v_exp_f32_e32 v175, v175
	v_pk_add_f32 v[168:169], v[168:169], v[250:251] op_sel_hi:[1,0] neg_lo:[0,1] neg_hi:[0,1]
	v_pk_add_f32 v[170:171], v[170:171], v[250:251] op_sel_hi:[1,0] neg_lo:[0,1] neg_hi:[0,1]
	v_pk_add_f32 v[172:173], v[172:173], 1.0 op_sel_hi:[1,0]
	v_pk_add_f32 v[174:175], v[174:175], 1.0 op_sel_hi:[1,0]
	v_pk_mul_f32 v[168:169], v[168:169], v[250:251] op_sel:[0,1] op_sel_hi:[1,1]
	v_pk_mul_f32 v[170:171], v[170:171], v[250:251] op_sel:[0,1] op_sel_hi:[1,1]
	v_rcp_f32_e32 v172, v172
	v_rcp_f32_e32 v173, v173
	v_rcp_f32_e32 v174, v174
	v_rcp_f32_e32 v175, v175
	v_pk_mul_f32 v[168:169], v[148:149], v[168:169]
	v_pk_mul_f32 v[170:171], v[150:151], v[170:171]
	v_pk_mul_f32 v[172:173], v[28:29], v[172:173]
	v_pk_mul_f32 v[174:175], v[30:31], v[174:175]
	v_pk_mul_f32 v[168:169], v[172:173], v[168:169]
	v_pk_mul_f32 v[170:171], v[174:175], v[170:171]
	v_cvt_pk_bf16_f32 v214, v168, v169
	v_cvt_pk_bf16_f32 v215, v170, v171
	v_lshlrev_b32_e32 v168, 16, v216
	v_and_b32_e32 v169, 0xffff0000, v216
	v_lshlrev_b32_e32 v170, 16, v217
	v_and_b32_e32 v171, 0xffff0000, v217
	v_mul_f32_e32 v172, 0xbfb8aa3b, v24
	v_mul_f32_e32 v173, 0xbfb8aa3b, v25
	v_mul_f32_e32 v174, 0xbfb8aa3b, v26
	v_mul_f32_e32 v175, 0xbfb8aa3b, v27
	v_exp_f32_e32 v172, v172
	v_exp_f32_e32 v173, v173
	v_exp_f32_e32 v174, v174
	v_exp_f32_e32 v175, v175
	v_pk_add_f32 v[168:169], v[168:169], v[250:251] op_sel_hi:[1,0] neg_lo:[0,1] neg_hi:[0,1]
	v_pk_add_f32 v[170:171], v[170:171], v[250:251] op_sel_hi:[1,0] neg_lo:[0,1] neg_hi:[0,1]
	v_pk_add_f32 v[172:173], v[172:173], 1.0 op_sel_hi:[1,0]
	v_pk_add_f32 v[174:175], v[174:175], 1.0 op_sel_hi:[1,0]
	v_pk_mul_f32 v[168:169], v[168:169], v[250:251] op_sel:[0,1] op_sel_hi:[1,1]
	v_pk_mul_f32 v[170:171], v[170:171], v[250:251] op_sel:[0,1] op_sel_hi:[1,1]
	v_rcp_f32_e32 v172, v172
	v_rcp_f32_e32 v173, v173
	v_rcp_f32_e32 v174, v174
	v_rcp_f32_e32 v175, v175
	v_pk_mul_f32 v[168:169], v[152:153], v[168:169]
	v_pk_mul_f32 v[170:171], v[154:155], v[170:171]
	v_pk_mul_f32 v[172:173], v[24:25], v[172:173]
	v_pk_mul_f32 v[174:175], v[26:27], v[174:175]
	v_pk_mul_f32 v[168:169], v[172:173], v[168:169]
	v_pk_mul_f32 v[170:171], v[174:175], v[170:171]
	v_cvt_pk_bf16_f32 v216, v168, v169
	v_cvt_pk_bf16_f32 v217, v170, v171
	v_add_u32_e32 v156, 0x80000, v116
	global_store_dwordx4 v156, v[214:217], s[6:7] offset:256
	s_waitcnt vmcnt(15)
	v_lshlrev_b32_e32 v168, 16, v218
	v_and_b32_e32 v169, 0xffff0000, v218
	v_lshlrev_b32_e32 v170, 16, v219
	v_and_b32_e32 v171, 0xffff0000, v219
	v_mul_f32_e32 v172, 0xbfb8aa3b, v84
	v_mul_f32_e32 v173, 0xbfb8aa3b, v85
	v_mul_f32_e32 v174, 0xbfb8aa3b, v86
	v_mul_f32_e32 v175, 0xbfb8aa3b, v87
	v_exp_f32_e32 v172, v172
	v_exp_f32_e32 v173, v173
	v_exp_f32_e32 v174, v174
	v_exp_f32_e32 v175, v175
	v_pk_add_f32 v[168:169], v[168:169], v[252:253] op_sel_hi:[1,0] neg_lo:[0,1] neg_hi:[0,1]
	v_pk_add_f32 v[170:171], v[170:171], v[252:253] op_sel_hi:[1,0] neg_lo:[0,1] neg_hi:[0,1]
	v_pk_add_f32 v[172:173], v[172:173], 1.0 op_sel_hi:[1,0]
	v_pk_add_f32 v[174:175], v[174:175], 1.0 op_sel_hi:[1,0]
	v_pk_mul_f32 v[168:169], v[168:169], v[252:253] op_sel:[0,1] op_sel_hi:[1,1]
	v_pk_mul_f32 v[170:171], v[170:171], v[252:253] op_sel:[0,1] op_sel_hi:[1,1]
	v_rcp_f32_e32 v172, v172
	v_rcp_f32_e32 v173, v173
	v_rcp_f32_e32 v174, v174
	v_rcp_f32_e32 v175, v175
	v_pk_mul_f32 v[168:169], v[140:141], v[168:169]
	v_pk_mul_f32 v[170:171], v[142:143], v[170:171]
	v_pk_mul_f32 v[172:173], v[84:85], v[172:173]
	v_pk_mul_f32 v[174:175], v[86:87], v[174:175]
	v_pk_mul_f32 v[168:169], v[172:173], v[168:169]
	v_pk_mul_f32 v[170:171], v[174:175], v[170:171]
	v_cvt_pk_bf16_f32 v218, v168, v169
	v_cvt_pk_bf16_f32 v219, v170, v171
	v_lshlrev_b32_e32 v168, 16, v220
	v_and_b32_e32 v169, 0xffff0000, v220
	v_lshlrev_b32_e32 v170, 16, v221
	v_and_b32_e32 v171, 0xffff0000, v221
	v_mul_f32_e32 v172, 0xbfb8aa3b, v80
	v_mul_f32_e32 v173, 0xbfb8aa3b, v81
	v_mul_f32_e32 v174, 0xbfb8aa3b, v82
	v_mul_f32_e32 v175, 0xbfb8aa3b, v83
	v_exp_f32_e32 v172, v172
	v_exp_f32_e32 v173, v173
	v_exp_f32_e32 v174, v174
	v_exp_f32_e32 v175, v175
	v_pk_add_f32 v[168:169], v[168:169], v[252:253] op_sel_hi:[1,0] neg_lo:[0,1] neg_hi:[0,1]
	v_pk_add_f32 v[170:171], v[170:171], v[252:253] op_sel_hi:[1,0] neg_lo:[0,1] neg_hi:[0,1]
	v_pk_add_f32 v[172:173], v[172:173], 1.0 op_sel_hi:[1,0]
	v_pk_add_f32 v[174:175], v[174:175], 1.0 op_sel_hi:[1,0]
	v_pk_mul_f32 v[168:169], v[168:169], v[252:253] op_sel:[0,1] op_sel_hi:[1,1]
	v_pk_mul_f32 v[170:171], v[170:171], v[252:253] op_sel:[0,1] op_sel_hi:[1,1]
	v_rcp_f32_e32 v172, v172
	v_rcp_f32_e32 v173, v173
	v_rcp_f32_e32 v174, v174
	v_rcp_f32_e32 v175, v175
	v_pk_mul_f32 v[168:169], v[144:145], v[168:169]
	v_pk_mul_f32 v[170:171], v[146:147], v[170:171]
	v_pk_mul_f32 v[172:173], v[80:81], v[172:173]
	v_pk_mul_f32 v[174:175], v[82:83], v[174:175]
	v_pk_mul_f32 v[168:169], v[172:173], v[168:169]
	v_pk_mul_f32 v[170:171], v[174:175], v[170:171]
	v_cvt_pk_bf16_f32 v220, v168, v169
	v_cvt_pk_bf16_f32 v221, v170, v171
	v_add_u32_e32 v156, 0x90000, v116
	global_store_dwordx4 v156, v[218:221], s[6:7]
	s_waitcnt vmcnt(15)
; __device__ __forceinline__ float fsilu(float x) { return x * fsig(x); }
; __device__ __forceinline__ u32x4 pack8(const f32x4 a, const f32x4 b) { u32x4 w; w.x = pk2(a[0], a[1]); w.y = pk2(a[2], a[3]); w.z = pk2(b[0], b[1]); w.w = pk2(b[2], b[3]); return w; }
; __device__ __forceinline__ void unpack8(const u32x4 w, f32x4& a, f32x4& b) { a[0] = bflo(w.x); a[1] = bfhi(w.x); a[2] = bflo(w.y); a[3] = bfhi(w.y); b[0] = bflo(w.z); b[1] = bfhi(w.z); b[2] = bflo(w.w); b[3] = bfhi(w.w); }
;     __device__ __forceinline__ bool operator()(EPI_ARGS) const {
;     ...
;                     for (int m2 = 0; m2 < 2; ++m2) {
;                         const int m = mh + m2;
;                         const size_t row = (size_t)u.pm * 256 + ROWLOC(ai, m);
;                         f32x4 v0, v1; unpack8(raw[m2], v0, v1);
;                         f32x4 r0, r1;
; #pragma unroll
;                         for (int e = 0; e < 4; ++e) { r0[e] = fsilu(acc[ai][bj][m][0][e]) * ((v0[e] - st[m2].x) * st[m2].y * w0[e]); r1[e] = fsilu(acc[ai][bj][m][1][e]) * ((v1[e] - st[m2].x) * st[m2].y * w1[e]); }
;                         *(u32x4*)(o + row * 2048 + col) = pack8(r0, r1);
	v_lshlrev_b32_e32 v168, 16, v222
	v_and_b32_e32 v169, 0xffff0000, v222
	v_lshlrev_b32_e32 v170, 16, v223
	v_and_b32_e32 v171, 0xffff0000, v223
	v_mul_f32_e32 v172, 0xbfb8aa3b, v20
	v_mul_f32_e32 v173, 0xbfb8aa3b, v21
	v_mul_f32_e32 v174, 0xbfb8aa3b, v22
	v_mul_f32_e32 v175, 0xbfb8aa3b, v23
	v_exp_f32_e32 v172, v172
	v_exp_f32_e32 v173, v173
	v_exp_f32_e32 v174, v174
	v_exp_f32_e32 v175, v175
	v_pk_add_f32 v[168:169], v[168:169], v[252:253] op_sel_hi:[1,0] neg_lo:[0,1] neg_hi:[0,1]
	v_pk_add_f32 v[170:171], v[170:171], v[252:253] op_sel_hi:[1,0] neg_lo:[0,1] neg_hi:[0,1]
	v_pk_add_f32 v[172:173], v[172:173], 1.0 op_sel_hi:[1,0]
	v_pk_add_f32 v[174:175], v[174:175], 1.0 op_sel_hi:[1,0]
	v_pk_mul_f32 v[168:169], v[168:169], v[252:253] op_sel:[0,1] op_sel_hi:[1,1]
	v_pk_mul_f32 v[170:171], v[170:171], v[252:253] op_sel:[0,1] op_sel_hi:[1,1]
	v_rcp_f32_e32 v172, v172
	v_rcp_f32_e32 v173, v173
	v_rcp_f32_e32 v174, v174
	v_rcp_f32_e32 v175, v175
	v_pk_mul_f32 v[168:169], v[148:149], v[168:169]
	v_pk_mul_f32 v[170:171], v[150:151], v[170:171]
	v_pk_mul_f32 v[172:173], v[20:21], v[172:173]
	v_pk_mul_f32 v[174:175], v[22:23], v[174:175]
	v_pk_mul_f32 v[168:169], v[172:173], v[168:169]
	v_pk_mul_f32 v[170:171], v[174:175], v[170:171]
	v_cvt_pk_bf16_f32 v222, v168, v169
	v_cvt_pk_bf16_f32 v223, v170, v171
	v_lshlrev_b32_e32 v168, 16, v224
	v_and_b32_e32 v169, 0xffff0000, v224
	v_lshlrev_b32_e32 v170, 16, v225
	v_and_b32_e32 v171, 0xffff0000, v225
	v_mul_f32_e32 v172, 0xbfb8aa3b, v16
	v_mul_f32_e32 v173, 0xbfb8aa3b, v17
	v_mul_f32_e32 v174, 0xbfb8aa3b, v18
	v_mul_f32_e32 v175, 0xbfb8aa3b, v19
	v_exp_f32_e32 v172, v172
	v_exp_f32_e32 v173, v173
	v_exp_f32_e32 v174, v174
	v_exp_f32_e32 v175, v175
	v_pk_add_f32 v[168:169], v[168:169], v[252:253] op_sel_hi:[1,0] neg_lo:[0,1] neg_hi:[0,1]
	v_pk_add_f32 v[170:171], v[170:171], v[252:253] op_sel_hi:[1,0] neg_lo:[0,1] neg_hi:[0,1]
	v_pk_add_f32 v[172:173], v[172:173], 1.0 op_sel_hi:[1,0]
	v_pk_add_f32 v[174:175], v[174:175], 1.0 op_sel_hi:[1,0]
	v_pk_mul_f32 v[168:169], v[168:169], v[252:253] op_sel:[0,1] op_sel_hi:[1,1]
	v_pk_mul_f32 v[170:171], v[170:171], v[252:253] op_sel:[0,1] op_sel_hi:[1,1]
	v_rcp_f32_e32 v172, v172
	v_rcp_f32_e32 v173, v173
	v_rcp_f32_e32 v174, v174
	v_rcp_f32_e32 v175, v175
	v_pk_mul_f32 v[168:169], v[152:153], v[168:169]
	v_pk_mul_f32 v[170:171], v[154:155], v[170:171]
	v_pk_mul_f32 v[172:173], v[16:17], v[172:173]
	v_pk_mul_f32 v[174:175], v[18:19], v[174:175]
	v_pk_mul_f32 v[168:169], v[172:173], v[168:169]
	v_pk_mul_f32 v[170:171], v[174:175], v[170:171]
	v_cvt_pk_bf16_f32 v224, v168, v169
	v_cvt_pk_bf16_f32 v225, v170, v171
	v_add_u32_e32 v156, 0x90000, v116
	global_store_dwordx4 v156, v[222:225], s[6:7] offset:256
	s_waitcnt vmcnt(15)
	v_lshlrev_b32_e32 v168, 16, v226
	v_and_b32_e32 v169, 0xffff0000, v226
	v_lshlrev_b32_e32 v170, 16, v227
	v_and_b32_e32 v171, 0xffff0000, v227
	v_mul_f32_e32 v172, 0xbfb8aa3b, v76
	v_mul_f32_e32 v173, 0xbfb8aa3b, v77
	v_mul_f32_e32 v174, 0xbfb8aa3b, v78
	v_mul_f32_e32 v175, 0xbfb8aa3b, v79
	v_exp_f32_e32 v172, v172
	v_exp_f32_e32 v173, v173
	v_exp_f32_e32 v174, v174
	v_exp_f32_e32 v175, v175
	v_pk_add_f32 v[168:169], v[168:169], v[112:113] op_sel_hi:[1,0] neg_lo:[0,1] neg_hi:[0,1]
	v_pk_add_f32 v[170:171], v[170:171], v[112:113] op_sel_hi:[1,0] neg_lo:[0,1] neg_hi:[0,1]
	v_pk_add_f32 v[172:173], v[172:173], 1.0 op_sel_hi:[1,0]
	v_pk_add_f32 v[174:175], v[174:175], 1.0 op_sel_hi:[1,0]
	v_pk_mul_f32 v[168:169], v[168:169], v[112:113] op_sel:[0,1] op_sel_hi:[1,1]
	v_pk_mul_f32 v[170:171], v[170:171], v[112:113] op_sel:[0,1] op_sel_hi:[1,1]
	v_rcp_f32_e32 v172, v172
	v_rcp_f32_e32 v173, v173
	v_rcp_f32_e32 v174, v174
	v_rcp_f32_e32 v175, v175
	v_pk_mul_f32 v[168:169], v[140:141], v[168:169]
	v_pk_mul_f32 v[170:171], v[142:143], v[170:171]
	v_pk_mul_f32 v[172:173], v[76:77], v[172:173]
	v_pk_mul_f32 v[174:175], v[78:79], v[174:175]
	v_pk_mul_f32 v[168:169], v[172:173], v[168:169]
	v_pk_mul_f32 v[170:171], v[174:175], v[170:171]
	v_cvt_pk_bf16_f32 v226, v168, v169
	v_cvt_pk_bf16_f32 v227, v170, v171
	v_lshlrev_b32_e32 v168, 16, v228
	v_and_b32_e32 v169, 0xffff0000, v228
	v_lshlrev_b32_e32 v170, 16, v229
	v_and_b32_e32 v171, 0xffff0000, v229
	v_mul_f32_e32 v172, 0xbfb8aa3b, v72
	v_mul_f32_e32 v173, 0xbfb8aa3b, v73
	v_mul_f32_e32 v174, 0xbfb8aa3b, v74
	v_mul_f32_e32 v175, 0xbfb8aa3b, v75
	v_exp_f32_e32 v172, v172
	v_exp_f32_e32 v173, v173
	v_exp_f32_e32 v174, v174
	v_exp_f32_e32 v175, v175
	v_pk_add_f32 v[168:169], v[168:169], v[112:113] op_sel_hi:[1,0] neg_lo:[0,1] neg_hi:[0,1]
	v_pk_add_f32 v[170:171], v[170:171], v[112:113] op_sel_hi:[1,0] neg_lo:[0,1] neg_hi:[0,1]
	v_pk_add_f32 v[172:173], v[172:173], 1.0 op_sel_hi:[1,0]
	v_pk_add_f32 v[174:175], v[174:175], 1.0 op_sel_hi:[1,0]
	v_pk_mul_f32 v[168:169], v[168:169], v[112:113] op_sel:[0,1] op_sel_hi:[1,1]
	v_pk_mul_f32 v[170:171], v[170:171], v[112:113] op_sel:[0,1] op_sel_hi:[1,1]
	v_rcp_f32_e32 v172, v172
	v_rcp_f32_e32 v173, v173
	v_rcp_f32_e32 v174, v174
	v_rcp_f32_e32 v175, v175
	v_pk_mul_f32 v[168:169], v[144:145], v[168:169]
	v_pk_mul_f32 v[170:171], v[146:147], v[170:171]
	v_pk_mul_f32 v[172:173], v[72:73], v[172:173]
	v_pk_mul_f32 v[174:175], v[74:75], v[174:175]
	v_pk_mul_f32 v[168:169], v[172:173], v[168:169]
	v_pk_mul_f32 v[170:171], v[174:175], v[170:171]
	v_cvt_pk_bf16_f32 v228, v168, v169
	v_cvt_pk_bf16_f32 v229, v170, v171
	v_add_u32_e32 v156, 0xa0000, v116
	global_store_dwordx4 v156, v[226:229], s[6:7]
	s_waitcnt vmcnt(15)
; __device__ __forceinline__ float fsilu(float x) { return x * fsig(x); }
; __device__ __forceinline__ u32x4 pack8(const f32x4 a, const f32x4 b) { u32x4 w; w.x = pk2(a[0], a[1]); w.y = pk2(a[2], a[3]); w.z = pk2(b[0], b[1]); w.w = pk2(b[2], b[3]); return w; }
; __device__ __forceinline__ void unpack8(const u32x4 w, f32x4& a, f32x4& b) { a[0] = bflo(w.x); a[1] = bfhi(w.x); a[2] = bflo(w.y); a[3] = bfhi(w.y); b[0] = bflo(w.z); b[1] = bfhi(w.z); b[2] = bflo(w.w); b[3] = bfhi(w.w); }
;     __device__ __forceinline__ bool operator()(EPI_ARGS) const {
;     ...
;                     for (int m2 = 0; m2 < 2; ++m2) {
;                         const int m = mh + m2;
;                         const size_t row = (size_t)u.pm * 256 + ROWLOC(ai, m);
;                         f32x4 v0, v1; unpack8(raw[m2], v0, v1);
;                         f32x4 r0, r1;
; #pragma unroll
;                         for (int e = 0; e < 4; ++e) { r0[e] = fsilu(acc[ai][bj][m][0][e]) * ((v0[e] - st[m2].x) * st[m2].y * w0[e]); r1[e] = fsilu(acc[ai][bj][m][1][e]) * ((v1[e] - st[m2].x) * st[m2].y * w1[e]); }
;                         *(u32x4*)(o + row * 2048 + col) = pack8(r0, r1);
	v_lshlrev_b32_e32 v168, 16, v230
	v_and_b32_e32 v169, 0xffff0000, v230
	v_lshlrev_b32_e32 v170, 16, v231
	v_and_b32_e32 v171, 0xffff0000, v231
	v_mul_f32_e32 v172, 0xbfb8aa3b, v12
	v_mul_f32_e32 v173, 0xbfb8aa3b, v13
	v_mul_f32_e32 v174, 0xbfb8aa3b, v14
	v_mul_f32_e32 v175, 0xbfb8aa3b, v15
	v_exp_f32_e32 v172, v172
	v_exp_f32_e32 v173, v173
	v_exp_f32_e32 v174, v174
	v_exp_f32_e32 v175, v175
	v_pk_add_f32 v[168:169], v[168:169], v[112:113] op_sel_hi:[1,0] neg_lo:[0,1] neg_hi:[0,1]
	v_pk_add_f32 v[170:171], v[170:171], v[112:113] op_sel_hi:[1,0] neg_lo:[0,1] neg_hi:[0,1]
	v_pk_add_f32 v[172:173], v[172:173], 1.0 op_sel_hi:[1,0]
	v_pk_add_f32 v[174:175], v[174:175], 1.0 op_sel_hi:[1,0]
	v_pk_mul_f32 v[168:169], v[168:169], v[112:113] op_sel:[0,1] op_sel_hi:[1,1]
	v_pk_mul_f32 v[170:171], v[170:171], v[112:113] op_sel:[0,1] op_sel_hi:[1,1]
	v_rcp_f32_e32 v172, v172
	v_rcp_f32_e32 v173, v173
	v_rcp_f32_e32 v174, v174
	v_rcp_f32_e32 v175, v175
	v_pk_mul_f32 v[168:169], v[148:149], v[168:169]
	v_pk_mul_f32 v[170:171], v[150:151], v[170:171]
	v_pk_mul_f32 v[172:173], v[12:13], v[172:173]
	v_pk_mul_f32 v[174:175], v[14:15], v[174:175]
	v_pk_mul_f32 v[168:169], v[172:173], v[168:169]
	v_pk_mul_f32 v[170:171], v[174:175], v[170:171]
	v_cvt_pk_bf16_f32 v230, v168, v169
	v_cvt_pk_bf16_f32 v231, v170, v171
	v_lshlrev_b32_e32 v168, 16, v232
	v_and_b32_e32 v169, 0xffff0000, v232
	v_lshlrev_b32_e32 v170, 16, v233
	v_and_b32_e32 v171, 0xffff0000, v233
	v_mul_f32_e32 v172, 0xbfb8aa3b, v8
	v_mul_f32_e32 v173, 0xbfb8aa3b, v9
	v_mul_f32_e32 v174, 0xbfb8aa3b, v10
	v_mul_f32_e32 v175, 0xbfb8aa3b, v11
	v_exp_f32_e32 v172, v172
	v_exp_f32_e32 v173, v173
	v_exp_f32_e32 v174, v174
	v_exp_f32_e32 v175, v175
	v_pk_add_f32 v[168:169], v[168:169], v[112:113] op_sel_hi:[1,0] neg_lo:[0,1] neg_hi:[0,1]
	v_pk_add_f32 v[170:171], v[170:171], v[112:113] op_sel_hi:[1,0] neg_lo:[0,1] neg_hi:[0,1]
	v_pk_add_f32 v[172:173], v[172:173], 1.0 op_sel_hi:[1,0]
	v_pk_add_f32 v[174:175], v[174:175], 1.0 op_sel_hi:[1,0]
	v_pk_mul_f32 v[168:169], v[168:169], v[112:113] op_sel:[0,1] op_sel_hi:[1,1]
	v_pk_mul_f32 v[170:171], v[170:171], v[112:113] op_sel:[0,1] op_sel_hi:[1,1]
	v_rcp_f32_e32 v172, v172
	v_rcp_f32_e32 v173, v173
	v_rcp_f32_e32 v174, v174
	v_rcp_f32_e32 v175, v175
	v_pk_mul_f32 v[168:169], v[152:153], v[168:169]
	v_pk_mul_f32 v[170:171], v[154:155], v[170:171]
	v_pk_mul_f32 v[172:173], v[8:9], v[172:173]
	v_pk_mul_f32 v[174:175], v[10:11], v[174:175]
	v_pk_mul_f32 v[168:169], v[172:173], v[168:169]
	v_pk_mul_f32 v[170:171], v[174:175], v[170:171]
	v_cvt_pk_bf16_f32 v232, v168, v169
	v_cvt_pk_bf16_f32 v233, v170, v171
	v_add_u32_e32 v156, 0xa0000, v116
	global_store_dwordx4 v156, v[230:233], s[6:7] offset:256
	s_waitcnt vmcnt(15)
	v_lshlrev_b32_e32 v168, 16, v234
	v_and_b32_e32 v169, 0xffff0000, v234
	v_lshlrev_b32_e32 v170, 16, v235
	v_and_b32_e32 v171, 0xffff0000, v235
	v_mul_f32_e32 v172, 0xbfb8aa3b, v68
	v_mul_f32_e32 v173, 0xbfb8aa3b, v69
	v_mul_f32_e32 v174, 0xbfb8aa3b, v70
	v_mul_f32_e32 v175, 0xbfb8aa3b, v71
	v_exp_f32_e32 v172, v172
	v_exp_f32_e32 v173, v173
	v_exp_f32_e32 v174, v174
	v_exp_f32_e32 v175, v175
	v_pk_add_f32 v[168:169], v[168:169], v[114:115] op_sel_hi:[1,0] neg_lo:[0,1] neg_hi:[0,1]
	v_pk_add_f32 v[170:171], v[170:171], v[114:115] op_sel_hi:[1,0] neg_lo:[0,1] neg_hi:[0,1]
	v_pk_add_f32 v[172:173], v[172:173], 1.0 op_sel_hi:[1,0]
	v_pk_add_f32 v[174:175], v[174:175], 1.0 op_sel_hi:[1,0]
	v_pk_mul_f32 v[168:169], v[168:169], v[114:115] op_sel:[0,1] op_sel_hi:[1,1]
	v_pk_mul_f32 v[170:171], v[170:171], v[114:115] op_sel:[0,1] op_sel_hi:[1,1]
	v_rcp_f32_e32 v172, v172
	v_rcp_f32_e32 v173, v173
	v_rcp_f32_e32 v174, v174
	v_rcp_f32_e32 v175, v175
	v_pk_mul_f32 v[168:169], v[140:141], v[168:169]
	v_pk_mul_f32 v[170:171], v[142:143], v[170:171]
	v_pk_mul_f32 v[172:173], v[68:69], v[172:173]
	v_pk_mul_f32 v[174:175], v[70:71], v[174:175]
	v_pk_mul_f32 v[168:169], v[172:173], v[168:169]
	v_pk_mul_f32 v[170:171], v[174:175], v[170:171]
	v_cvt_pk_bf16_f32 v234, v168, v169
	v_cvt_pk_bf16_f32 v235, v170, v171
	v_lshlrev_b32_e32 v168, 16, v236
	v_and_b32_e32 v169, 0xffff0000, v236
	v_lshlrev_b32_e32 v170, 16, v237
	v_and_b32_e32 v171, 0xffff0000, v237
	v_mul_f32_e32 v172, 0xbfb8aa3b, v64
	v_mul_f32_e32 v173, 0xbfb8aa3b, v65
	v_mul_f32_e32 v174, 0xbfb8aa3b, v66
	v_mul_f32_e32 v175, 0xbfb8aa3b, v67
	v_exp_f32_e32 v172, v172
	v_exp_f32_e32 v173, v173
	v_exp_f32_e32 v174, v174
	v_exp_f32_e32 v175, v175
	v_pk_add_f32 v[168:169], v[168:169], v[114:115] op_sel_hi:[1,0] neg_lo:[0,1] neg_hi:[0,1]
	v_pk_add_f32 v[170:171], v[170:171], v[114:115] op_sel_hi:[1,0] neg_lo:[0,1] neg_hi:[0,1]
	v_pk_add_f32 v[172:173], v[172:173], 1.0 op_sel_hi:[1,0]
	v_pk_add_f32 v[174:175], v[174:175], 1.0 op_sel_hi:[1,0]
	v_pk_mul_f32 v[168:169], v[168:169], v[114:115] op_sel:[0,1] op_sel_hi:[1,1]
	v_pk_mul_f32 v[170:171], v[170:171], v[114:115] op_sel:[0,1] op_sel_hi:[1,1]
	v_rcp_f32_e32 v172, v172
	v_rcp_f32_e32 v173, v173
	v_rcp_f32_e32 v174, v174
	v_rcp_f32_e32 v175, v175
	v_pk_mul_f32 v[168:169], v[144:145], v[168:169]
	v_pk_mul_f32 v[170:171], v[146:147], v[170:171]
	v_pk_mul_f32 v[172:173], v[64:65], v[172:173]
	v_pk_mul_f32 v[174:175], v[66:67], v[174:175]
	v_pk_mul_f32 v[168:169], v[172:173], v[168:169]
	v_pk_mul_f32 v[170:171], v[174:175], v[170:171]
	v_cvt_pk_bf16_f32 v236, v168, v169
	v_cvt_pk_bf16_f32 v237, v170, v171
	v_add_u32_e32 v156, 0xb0000, v116
	global_store_dwordx4 v156, v[234:237], s[6:7]
	s_waitcnt vmcnt(15)
; __device__ __forceinline__ float fsilu(float x) { return x * fsig(x); }
; __device__ __forceinline__ u32x4 pack8(const f32x4 a, const f32x4 b) { u32x4 w; w.x = pk2(a[0], a[1]); w.y = pk2(a[2], a[3]); w.z = pk2(b[0], b[1]); w.w = pk2(b[2], b[3]); return w; }
; __device__ __forceinline__ void unpack8(const u32x4 w, f32x4& a, f32x4& b) { a[0] = bflo(w.x); a[1] = bfhi(w.x); a[2] = bflo(w.y); a[3] = bfhi(w.y); b[0] = bflo(w.z); b[1] = bfhi(w.z); b[2] = bflo(w.w); b[3] = bfhi(w.w); }
;     __device__ __forceinline__ bool operator()(EPI_ARGS) const {
;     ...
;                     for (int m2 = 0; m2 < 2; ++m2) {
;                         const int m = mh + m2;
;                         const size_t row = (size_t)u.pm * 256 + ROWLOC(ai, m);
;                         f32x4 v0, v1; unpack8(raw[m2], v0, v1);
;                         f32x4 r0, r1;
; #pragma unroll
;                         for (int e = 0; e < 4; ++e) { r0[e] = fsilu(acc[ai][bj][m][0][e]) * ((v0[e] - st[m2].x) * st[m2].y * w0[e]); r1[e] = fsilu(acc[ai][bj][m][1][e]) * ((v1[e] - st[m2].x) * st[m2].y * w1[e]); }
;                         *(u32x4*)(o + row * 2048 + col) = pack8(r0, r1);
	v_lshlrev_b32_e32 v168, 16, v238
	v_and_b32_e32 v169, 0xffff0000, v238
	v_lshlrev_b32_e32 v170, 16, v239
	v_and_b32_e32 v171, 0xffff0000, v239
	v_mul_f32_e32 v172, 0xbfb8aa3b, v4
	v_mul_f32_e32 v173, 0xbfb8aa3b, v5
	v_mul_f32_e32 v174, 0xbfb8aa3b, v6
	v_mul_f32_e32 v175, 0xbfb8aa3b, v7
	v_exp_f32_e32 v172, v172
	v_exp_f32_e32 v173, v173
	v_exp_f32_e32 v174, v174
	v_exp_f32_e32 v175, v175
	v_pk_add_f32 v[168:169], v[168:169], v[114:115] op_sel_hi:[1,0] neg_lo:[0,1] neg_hi:[0,1]
	v_pk_add_f32 v[170:171], v[170:171], v[114:115] op_sel_hi:[1,0] neg_lo:[0,1] neg_hi:[0,1]
	v_pk_add_f32 v[172:173], v[172:173], 1.0 op_sel_hi:[1,0]
	v_pk_add_f32 v[174:175], v[174:175], 1.0 op_sel_hi:[1,0]
	v_pk_mul_f32 v[168:169], v[168:169], v[114:115] op_sel:[0,1] op_sel_hi:[1,1]
	v_pk_mul_f32 v[170:171], v[170:171], v[114:115] op_sel:[0,1] op_sel_hi:[1,1]
	v_rcp_f32_e32 v172, v172
	v_rcp_f32_e32 v173, v173
	v_rcp_f32_e32 v174, v174
	v_rcp_f32_e32 v175, v175
	v_pk_mul_f32 v[168:169], v[148:149], v[168:169]
	v_pk_mul_f32 v[170:171], v[150:151], v[170:171]
	v_pk_mul_f32 v[172:173], v[4:5], v[172:173]
	v_pk_mul_f32 v[174:175], v[6:7], v[174:175]
	v_pk_mul_f32 v[168:169], v[172:173], v[168:169]
	v_pk_mul_f32 v[170:171], v[174:175], v[170:171]
	v_cvt_pk_bf16_f32 v238, v168, v169
	v_cvt_pk_bf16_f32 v239, v170, v171
	v_lshlrev_b32_e32 v168, 16, v240
	v_and_b32_e32 v169, 0xffff0000, v240
	v_lshlrev_b32_e32 v170, 16, v241
	v_and_b32_e32 v171, 0xffff0000, v241
	v_mul_f32_e32 v172, 0xbfb8aa3b, v0
	v_mul_f32_e32 v173, 0xbfb8aa3b, v1
	v_mul_f32_e32 v174, 0xbfb8aa3b, v2
	v_mul_f32_e32 v175, 0xbfb8aa3b, v3
	v_exp_f32_e32 v172, v172
	v_exp_f32_e32 v173, v173
	v_exp_f32_e32 v174, v174
	v_exp_f32_e32 v175, v175
	v_pk_add_f32 v[168:169], v[168:169], v[114:115] op_sel_hi:[1,0] neg_lo:[0,1] neg_hi:[0,1]
	v_pk_add_f32 v[170:171], v[170:171], v[114:115] op_sel_hi:[1,0] neg_lo:[0,1] neg_hi:[0,1]
	v_pk_add_f32 v[172:173], v[172:173], 1.0 op_sel_hi:[1,0]
	v_pk_add_f32 v[174:175], v[174:175], 1.0 op_sel_hi:[1,0]
	v_pk_mul_f32 v[168:169], v[168:169], v[114:115] op_sel:[0,1] op_sel_hi:[1,1]
	v_pk_mul_f32 v[170:171], v[170:171], v[114:115] op_sel:[0,1] op_sel_hi:[1,1]
	v_rcp_f32_e32 v172, v172
	v_rcp_f32_e32 v173, v173
	v_rcp_f32_e32 v174, v174
	v_rcp_f32_e32 v175, v175
	v_pk_mul_f32 v[168:169], v[152:153], v[168:169]
	v_pk_mul_f32 v[170:171], v[154:155], v[170:171]
	v_pk_mul_f32 v[172:173], v[0:1], v[172:173]
	v_pk_mul_f32 v[174:175], v[2:3], v[174:175]
	v_pk_mul_f32 v[168:169], v[172:173], v[168:169]
	v_pk_mul_f32 v[170:171], v[174:175], v[170:171]
	v_cvt_pk_bf16_f32 v240, v168, v169
	v_cvt_pk_bf16_f32 v241, v170, v171
	v_add_u32_e32 v156, 0xb0000, v116
	global_store_dwordx4 v156, v[238:241], s[6:7] offset:256
	s_andn2_b64 vcc, exec, s[8:9]
	s_mov_b64 s[8:9], -1
	s_cbranch_vccnz .LBB0_973
	s_andn2_b64 vcc, exec, s[12:13]
	s_cbranch_vccnz .LBB0_972
	s_barrier
	s_branch .LBB0_972
